# static first sparse-attention item order reversed: workgroups that reach phase Y first (high blockIdx) take the latest query tiles
# baseline (speedup 1.0000x reference)
; __device__ void phase_y(const Params& p, int layer, unsigned char* smem) {
;     ...
;   for (int i = blockIdx.x; i < NI / 2; i += G) {
; #pragma unroll 1
;     for (int h = 0; h < 2; ++h) {
;       int it = h ? (NI - 1 - i) : i;
;       int qt = 63 - (it >> 4); int r = it & 15; int b = r >> 1, g = r & 1;
.LBB0_33:
	s_and_b32 s0, s9, 7
	s_lshl_b32 s0, s0, 1
	s_bfe_u32 s1, s9, 0x10003
	s_or_b32 s0, s0, s1
	s_andn2_b32 s1, s9, 15
	s_or_b32 s0, s0, s1
	s_xor_b32 s0, s0, 0x1f0
	v_writelane_b32 v255, s0, 25
	s_xor_b32 s0, s0, 0x3f0
	v_writelane_b32 v255, s0, 24
	s_mov_b64 s[0:1], -1
	s_branch .LBB0_35
